# stack20 plus both GLA trims: SGPR-base output-store addressing and the dropped wave-uniform branch
# baseline (speedup 1.0000x reference)
.LBB0_233:
	ds_read_b64_tr_b16 v[134:135], v117 offset:576
	ds_read_b64_tr_b16 v[132:133], v117
	ds_read_b128 v[136:139], v125 offset:18432
	ds_read_b64_tr_b16 v[142:143], v117 offset:608
	ds_read_b64_tr_b16 v[140:141], v117 offset:32
	ds_read_b128 v[144:147], v125 offset:18496
	ds_read_b64_tr_b16 v[150:151], v117 offset:4608
	ds_read_b64_tr_b16 v[152:153], v117 offset:5184
	ds_read_b64_tr_b16 v[156:157], v117 offset:5216
	ds_read_b64_tr_b16 v[154:155], v117 offset:4640
	s_waitcnt lgkmcnt(7)
	v_mfma_f32_16x16x32_bf16 v[50:53], v[132:135], v[136:139], v[50:53]
	ds_read_b64_tr_b16 v[158:159], v101 offset:55296
	ds_read_b64_tr_b16 v[160:161], v101 offset:55872
	v_add_u32_e32 v131, v94, v97
	s_waitcnt lgkmcnt(7)
	v_mfma_f32_16x16x32_bf16 v[136:139], v[140:143], v[136:139], v[54:57]
	s_waitcnt lgkmcnt(4)
	v_mfma_f32_16x16x32_bf16 v[50:53], v[150:153], v[144:147], v[50:53]
	s_nop 0
	v_add_u32_e32 v56, s29, v71
	v_add_u32_e32 v54, 64, v129
	v_cndmask_b32_e64 v54, v54, v56, s[0:1]
	s_waitcnt lgkmcnt(2)
	v_mfma_f32_16x16x32_bf16 v[136:139], v[154:157], v[144:147], v[136:139]
	ds_read_b64_tr_b16 v[144:145], v101 offset:59904
	ds_read_b64_tr_b16 v[146:147], v101 offset:60480
	v_add_u32_e32 v54, s30, v54
	s_nop 0
	s_waitcnt lgkmcnt(2)
	v_mfma_f32_16x16x32_bf16 v[46:49], v[158:161], v[132:135], v[46:49]
	v_cvt_pk_bf16_f32 v172, v50, v51
	v_cvt_pk_bf16_f32 v173, v52, v53
	ds_read_b128 v[50:53], v118 offset:46080
	v_mfma_f32_16x16x32_bf16 v[42:45], v[158:161], v[140:143], v[42:45]
	v_lshl_add_u32 v54, v54, 10, v176
	s_nop 0
	s_nop 0
	s_waitcnt lgkmcnt(1)
	v_mfma_f32_16x16x32_bf16 v[46:49], v[144:147], v[150:153], v[46:49]
	v_cvt_pk_bf16_f32 v174, v136, v137
	v_cvt_pk_bf16_f32 v175, v138, v139
	s_nop 1
	v_permlane16_swap_b32_e32 v172, v174
	v_permlane16_swap_b32_e32 v173, v175
	global_store_dwordx4 v54, v[172:175], s[6:7]
	v_mfma_f32_16x16x32_bf16 v[42:45], v[144:147], v[154:157], v[42:45]
	s_waitcnt vmcnt(8)
	v_lshlrev_b32_e32 v136, 16, v22
	s_waitcnt lgkmcnt(0)
	s_nop 0
	v_pk_mul_f32 v[48:49], v[52:53], v[48:49]
	v_pk_mul_f32 v[46:47], v[50:51], v[46:47]
	v_and_b32_e32 v137, 0xffff0000, v22
	v_lshlrev_b32_e32 v22, 16, v23
	v_pk_mul_f32 v[44:45], v[52:53], v[44:45]
	v_pk_mul_f32 v[42:43], v[50:51], v[42:43]
	v_cvt_pk_bf16_f32 v50, v46, v47
	v_cvt_pk_bf16_f32 v51, v48, v49
	ds_write_b64 v131, v[50:51] offset:27648
	v_cvt_pk_bf16_f32 v50, v42, v43
	v_cvt_pk_bf16_f32 v51, v44, v45
	ds_write_b64 v119, v[50:51] offset:27648
	ds_read_b128 v[50:53], v120
	ds_read_b128 v[132:135], v120 offset:16
	v_and_b32_e32 v23, 0xffff0000, v23
	v_lshlrev_b32_e32 v138, 16, v24
	v_and_b32_e32 v139, 0xffff0000, v24
	s_waitcnt lgkmcnt(1)
	v_exp_f32_e64 v54, -v50
	v_exp_f32_e64 v55, -v51
	v_exp_f32_e32 v50, v50
	v_exp_f32_e32 v51, v51
	s_waitcnt lgkmcnt(0)
	v_exp_f32_e32 v24, v134
	v_pk_mul_f32 v[54:55], v[54:55], v[136:137]
	s_waitcnt vmcnt(6)
	v_lshlrev_b32_e32 v136, 16, v18
	v_and_b32_e32 v137, 0xffff0000, v18
	v_pk_mul_f32 v[136:137], v[50:51], v[136:137]
	s_nop 0
	v_cvt_pk_bf16_f32 v18, v136, v137
	v_cvt_pk_bf16_f32 v136, v54, v55
	v_exp_f32_e64 v54, -v52
	v_exp_f32_e64 v55, -v53
	v_exp_f32_e32 v52, v52
	v_exp_f32_e32 v53, v53
	v_pk_mul_f32 v[22:23], v[54:55], v[22:23]
	v_lshlrev_b32_e32 v54, 16, v19
	v_and_b32_e32 v55, 0xffff0000, v19
	v_pk_mul_f32 v[54:55], v[52:53], v[54:55]
	v_cvt_pk_bf16_f32 v137, v22, v23
	v_cvt_pk_bf16_f32 v19, v54, v55
	v_exp_f32_e64 v54, -v132
	v_exp_f32_e64 v55, -v133
	v_exp_f32_e32 v22, v132
	v_exp_f32_e32 v23, v133
	v_lshlrev_b32_e32 v132, 16, v20
	v_pk_mul_f32 v[54:55], v[54:55], v[138:139]
	v_and_b32_e32 v133, 0xffff0000, v20
	v_pk_mul_f32 v[132:133], v[22:23], v[132:133]
	v_cvt_pk_bf16_f32 v138, v54, v55
	v_exp_f32_e64 v54, -v134
	v_exp_f32_e64 v55, -v135
	v_cvt_pk_bf16_f32 v20, v132, v133
	v_lshlrev_b32_e32 v132, 16, v25
	v_and_b32_e32 v133, 0xffff0000, v25
	v_exp_f32_e32 v25, v135
	v_pk_mul_f32 v[54:55], v[54:55], v[132:133]
	v_lshlrev_b32_e32 v132, 16, v21
	v_and_b32_e32 v133, 0xffff0000, v21
	v_pk_mul_f32 v[132:133], v[24:25], v[132:133]
	v_cvt_pk_bf16_f32 v139, v54, v55
	v_cvt_pk_bf16_f32 v21, v132, v133
	ds_write_b128 v111, v[18:21]
	ds_write_b128 v111, v[136:139] offset:64512
	s_and_saveexec_b64 s[26:27], vcc
	ds_write_b128 v126, v[50:53] offset:46336
	ds_write_b128 v126, v[22:25] offset:46352
